# P3: half of the workgroups run their SSD sample units before the HGRN2 sample unit (de-lockstep of the sample stream)
# speedup vs baseline: 1.0049x; 1.0049x over previous
.LBB0_678:
	s_bfe_u32 s0, s2, 0x10003
	s_mov_b32 s1, 0
	v_writelane_b32 v255, s0, 7
	v_writelane_b32 v255, s1, 1
	v_writelane_b32 v255, s0, 2
	v_writelane_b32 v255, s90, 8
	v_writelane_b32 v255, s90, 9
	v_writelane_b32 v255, s90, 10
	v_writelane_b32 v255, s90, 11
	s_cmp_lt_i32 s92, 4
	s_cselect_b64 s[0:1], -1, 0
	s_cmp_gt_i32 s93, 3
	s_cselect_b64 s[4:5], -1, 0
	s_and_b64 s[0:1], s[0:1], s[4:5]
	s_andn2_b64 vcc, exec, s[0:1]
	s_cbranch_vccnz .LBB0_996

.LBB0_881:
	v_readlane_b32 vcc_lo, v255, 1
	s_cmp_lg_u32 vcc_lo, 0
	s_cbranch_scc1 .LBB0_942
	v_readlane_b32 s69, v255, 11
	s_mov_b64 s[0:1], -1
	s_add_i32 s4, s69, s88
	v_writelane_b32 v255, s4, 11
	s_cmpk_gt_i32 s69, 0x287
	s_cbranch_scc1 .LBB0_880
	s_cmpk_lt_i32 s69, 0x200
	s_cbranch_scc0 .LBB0_932
	s_and_b32 s15, s69, 3
	s_ashr_i32 s36, s69, 2
	s_lshl_b32 s10, s15, 3
	s_add_i32 s14, s33, s10
	s_lshl_b32 s0, s36, 5
	s_add_i32 s0, s14, s0
	s_ashr_i32 s37, s36, 31
	s_ashr_i32 s1, s0, 31
	v_readlane_b32 s52, v254, 9
	s_waitcnt vmcnt(4)
	v_mov_b32_e32 v164, v0
	s_lshl_b64 s[4:5], s[36:37], 2
	s_lshl_b64 s[6:7], s[0:1], 15
	v_readlane_b32 s58, v254, 15
	v_readlane_b32 s59, v254, 16
	v_bfe_u32 v167, v164, 5, 1
	s_add_u32 s6, s58, s6
	v_and_b32_e32 v168, 31, v164
	s_addc_u32 s7, s59, s7
	v_lshlrev_b32_e32 v140, 9, v167
	v_lshl_add_u64 v[2:3], s[6:7], 0, v[140:141]
	v_lshlrev_b32_e32 v140, 4, v168
	v_lshl_add_u64 v[94:95], v[2:3], 0, v[140:141]
	v_add_co_u32_e32 v2, vcc, s47, v94
	s_movk_i32 s6, 0x7000
	s_nop 0
	v_addc_co_u32_e32 v3, vcc, 0, v95, vcc
	s_waitcnt vmcnt(1)
	v_add_co_u32_e32 v110, vcc, s48, v94
	global_load_dwordx4 v[90:93], v[94:95], off nt
	global_load_dwordx4 v[86:89], v[94:95], off offset:1024 nt
	global_load_dwordx4 v[82:85], v[94:95], off offset:2048 nt
	global_load_dwordx4 v[78:81], v[94:95], off offset:3072 nt
	v_addc_co_u32_e32 v111, vcc, 0, v95, vcc
	v_add_co_u32_e32 v4, vcc, s49, v94
	global_load_dwordx4 v[74:77], v[2:3], off offset:1024 nt
	global_load_dwordx4 v[70:73], v[2:3], off offset:2048 nt
	global_load_dwordx4 v[66:69], v[110:111], off nt
	global_load_dwordx4 v[62:65], v[110:111], off offset:1024 nt
	global_load_dwordx4 v[58:61], v[110:111], off offset:2048 nt
	global_load_dwordx4 v[54:57], v[110:111], off offset:3072 nt
	v_addc_co_u32_e32 v5, vcc, 0, v95, vcc
	v_add_co_u32_e32 v6, vcc, s50, v94
	s_add_u32 s8, s4, 0x4000
	s_nop 0
	v_addc_co_u32_e32 v7, vcc, 0, v95, vcc
	v_add_co_u32_e32 v96, vcc, s51, v94
	global_load_dwordx4 v[122:125], v[2:3], off offset:3072 nt
	global_load_dwordx4 v[26:29], v[4:5], off offset:1024 nt
	global_load_dwordx4 v[22:25], v[4:5], off offset:2048 nt
	global_load_dwordx4 v[18:21], v[4:5], off offset:3072 nt
	global_load_dwordx4 v[106:109], v[6:7], off offset:-4096 nt
	global_load_dwordx4 v[50:53], v[6:7], off nt
	global_load_dwordx4 v[46:49], v[6:7], off offset:1024 nt
	global_load_dwordx4 v[42:45], v[6:7], off offset:2048 nt
	v_addc_co_u32_e32 v97, vcc, 0, v95, vcc
	s_waitcnt vmcnt(18)
	v_add_co_u32_e32 v38, vcc, s24, v94
	s_movk_i32 s4, 0x17f
	s_nop 0
	v_addc_co_u32_e32 v39, vcc, 0, v95, vcc
	global_load_dwordx4 v[114:117], v[6:7], off offset:3072 nt
	global_load_dwordx4 v[14:17], v[38:39], off offset:-4096 nt
	global_load_dwordx4 v[10:13], v[96:97], off offset:1024 nt
	s_nop 0
	global_load_dwordx4 v[6:9], v[96:97], off offset:2048 nt
	global_load_dwordx4 v[2:5], v[38:39], off nt
	global_load_dwordx4 v[30:33], v[38:39], off offset:1024 nt
	global_load_dwordx4 v[34:37], v[38:39], off offset:2048 nt
	s_nop 0
	global_load_dwordx4 v[38:41], v[38:39], off offset:3072 nt
	v_add_co_u32_e32 v112, vcc, s6, v94
	s_addc_u32 s9, s5, 0
	s_nop 0
	v_addc_co_u32_e32 v113, vcc, 0, v95, vcc
	global_load_dwordx4 v[118:121], v[96:97], off offset:3072 nt
	s_nop 0
	global_load_dwordx4 v[94:97], v[112:113], off nt
	global_load_dwordx4 v[98:101], v[112:113], off offset:1024 nt
	global_load_dwordx4 v[102:105], v[112:113], off offset:2048 nt
	global_load_dwordx4 v[126:129], v[110:111], off offset:-4096 nt
	s_nop 0
	global_load_dwordx4 v[110:113], v[112:113], off offset:3072 nt
	v_cmp_lt_i32_e32 vcc, s4, v164
	v_readlane_b32 s53, v254, 10
	v_readlane_b32 s54, v254, 11
	v_readlane_b32 s55, v254, 12
	v_readlane_b32 s56, v254, 13
	v_readlane_b32 s57, v254, 14
	v_readlane_b32 s60, v254, 17
	v_readlane_b32 s61, v254, 18
	v_readlane_b32 s62, v254, 19
	v_readlane_b32 s63, v254, 20
	v_readlane_b32 s64, v254, 21
	v_readlane_b32 s65, v254, 22
	v_readlane_b32 s66, v254, 23
	v_readlane_b32 s67, v254, 24
	s_and_saveexec_b64 s[4:5], vcc
	s_xor_b64 s[4:5], exec, s[4:5]
	s_cbranch_execz .LBB0_893
	s_movk_i32 s6, 0x1a0
	v_cmp_gt_u32_e32 vcc, s6, v164
	s_and_saveexec_b64 s[6:7], vcc
	s_cbranch_execz .LBB0_892
	v_and_or_b32 v130, v164, 3, s8
	v_mov_b32_e32 v131, s9
	v_lshlrev_b64 v[130:131], 7, v[130:131]
	v_add_u32_e32 v132, 0xfffffe80, v164
	v_lshl_add_u64 v[130:131], s[20:21], 0, v[130:131]
	s_lshl_b32 s18, s10, 2
	v_lshrrev_b32_e32 v133, 2, v132
	v_and_b32_e32 v140, -4, v132
	v_lshl_add_u64 v[130:131], v[130:131], 0, s[18:19]
	v_lshl_add_u64 v[130:131], v[130:131], 0, v[140:141]
	v_add_u32_e32 v140, s10, v133
	global_load_dword v132, v[130:131], off
	v_lshl_add_u64 v[130:131], v[140:141], 2, s[76:77]
	global_load_dword v130, v[130:131], off
	s_mov_b32 s10, 0x41a00000
	s_waitcnt vmcnt(0)
	v_add_f32_e32 v130, v132, v130
	v_cmp_nlt_f32_e32 vcc, s10, v130
	s_and_saveexec_b64 s[10:11], vcc
	s_cbranch_execz .LBB0_891
	v_mul_f32_e32 v130, 0x3fb8aa3b, v130
	v_exp_f32_e32 v139, v130
	s_mov_b32 s12, 0x3f2aaaab
	v_add_f32_e32 v132, 1.0, v139
	v_frexp_mant_f32_e32 v134, v132
	v_cvt_f64_f32_e32 v[130:131], v132
	v_frexp_exp_i32_f64_e32 v130, v[130:131]
	v_cmp_gt_f32_e32 vcc, s12, v134
	v_add_f32_e32 v133, -1.0, v132
	v_sub_f32_e32 v135, v133, v132
	v_subbrev_co_u32_e32 v140, vcc, 0, v130, vcc
	v_sub_u32_e32 v130, 0, v140
	v_sub_f32_e32 v133, v139, v133
	v_add_f32_e32 v135, 1.0, v135
	v_ldexp_f32 v131, v132, v130
	v_add_f32_e32 v133, v133, v135
	v_add_f32_e32 v132, -1.0, v131
	v_add_f32_e32 v134, 1.0, v131
	v_ldexp_f32 v130, v133, v130
	v_add_f32_e32 v133, 1.0, v132
	v_add_f32_e32 v135, -1.0, v134
	v_sub_f32_e32 v133, v131, v133
	v_sub_f32_e32 v131, v131, v135
	v_add_f32_e32 v133, v130, v133
	v_add_f32_e32 v130, v130, v131
	v_add_f32_e32 v143, v134, v130
	v_rcp_f32_e32 v145, v143
	v_sub_f32_e32 v131, v143, v134
	v_sub_f32_e32 v144, v130, v131
	v_add_f32_e32 v131, v132, v133
	v_mul_f32_e32 v147, v131, v145
	v_sub_f32_e32 v130, v131, v132
	v_mul_f32_e32 v132, v143, v147
	v_fma_f32 v134, v147, v143, -v132
	v_fmac_f32_e32 v134, v147, v144
	v_sub_f32_e32 v146, v133, v130
	v_add_f32_e32 v130, v132, v134
	v_sub_f32_e32 v133, v131, v130
	v_pk_add_f32 v[136:137], v[130:131], v[132:133] neg_lo:[0,1] neg_hi:[0,1]
	v_mov_b32_e32 v135, v130
	v_pk_add_f32 v[130:131], v[136:137], v[134:135] neg_lo:[0,1] neg_hi:[0,1]
	s_mov_b32 s12, 0x3f317218
	v_add_f32_e32 v131, v146, v131
	v_add_f32_e32 v130, v130, v131
	v_add_f32_e32 v131, v133, v130
	v_mul_f32_e32 v146, v145, v131
	v_mul_f32_e32 v132, v143, v146
	v_fma_f32 v134, v146, v143, -v132
	v_fmac_f32_e32 v134, v146, v144
	v_sub_f32_e32 v133, v133, v131
	v_add_f32_e32 v143, v130, v133
	v_add_f32_e32 v130, v132, v134
	v_sub_f32_e32 v133, v131, v130
	v_pk_add_f32 v[136:137], v[130:131], v[132:133] neg_lo:[0,1] neg_hi:[0,1]
	v_mov_b32_e32 v135, v130
	v_pk_add_f32 v[130:131], v[136:137], v[134:135] neg_lo:[0,1] neg_hi:[0,1]
	s_nop 0
	v_add_f32_e32 v131, v143, v131
	v_add_f32_e32 v130, v130, v131
	v_add_f32_e32 v131, v147, v146
	v_add_f32_e32 v130, v133, v130
	v_sub_f32_e32 v132, v131, v147
	v_mul_f32_e32 v130, v145, v130
	v_sub_f32_e32 v132, v146, v132
	v_add_f32_e32 v132, v132, v130
	v_add_f32_e32 v134, v131, v132
	v_mul_f32_e32 v135, v134, v134
	v_fmamk_f32 v130, v135, 0x3e9b6dac, v158
	v_fmaak_f32 v143, v135, v130, 0x3f2aaada
	v_cvt_f32_i32_e32 v130, v140
	v_sub_f32_e32 v131, v134, v131
	v_sub_f32_e32 v131, v132, v131
	v_ldexp_f32 v136, v131, 1
	v_mul_f32_e32 v131, v134, v135
	v_ldexp_f32 v133, v134, 1
	v_pk_mul_f32 v[134:135], v[130:131], v[142:143]
	s_nop 0
	v_fma_f32 v132, v130, s12, -v134
	v_fmac_f32_e32 v132, 0xb102e308, v130
	v_pk_add_f32 v[130:131], v[134:135], v[132:133]
	s_mov_b32 s12, 0x7f800000
	v_sub_f32_e32 v133, v131, v133
	v_sub_f32_e32 v133, v135, v133
	v_add_f32_e32 v137, v136, v133
	v_mov_b32_e32 v136, v134
	v_pk_add_f32 v[134:135], v[130:131], v[134:135] neg_lo:[0,1] neg_hi:[0,1]
	v_pk_add_f32 v[144:145], v[130:131], v[136:137]
	v_mov_b32_e32 v133, v130
	v_mov_b32_e32 v135, v145
	v_pk_add_f32 v[146:147], v[132:133], v[134:135] neg_lo:[0,1] neg_hi:[0,1]
	v_pk_add_f32 v[132:133], v[132:133], v[134:135]
	v_mov_b32_e32 v136, v137
	v_pk_add_f32 v[134:135], v[132:133], v[130:131] op_sel:[1,0] op_sel_hi:[0,1] neg_lo:[0,1] neg_hi:[0,1]
	v_pk_add_f32 v[148:149], v[144:145], v[134:135] op_sel_hi:[1,0] neg_lo:[0,1] neg_hi:[0,1]
	v_mov_b32_e32 v144, v145
	v_mov_b32_e32 v145, v133
	v_pk_mov_b32 v[134:135], v[130:131], v[134:135] op_sel:[1,0]
	v_mov_b32_e32 v137, v130
	v_pk_add_f32 v[134:135], v[144:145], v[134:135] neg_lo:[0,1] neg_hi:[0,1]
	v_mov_b32_e32 v148, v146
	v_pk_add_f32 v[130:131], v[136:137], v[134:135] neg_lo:[0,1] neg_hi:[0,1]
	v_mov_b32_e32 v147, v133
	v_pk_add_f32 v[134:135], v[148:149], v[130:131]
	v_cmp_neq_f32_e32 vcc, s12, v139
	v_pk_add_f32 v[136:137], v[134:135], v[134:135] op_sel:[0,1] op_sel_hi:[1,0]
	s_mov_b32 s12, 0x33800000
	v_pk_add_f32 v[132:133], v[132:133], v[136:137] op_sel:[1,0] op_sel_hi:[0,1]
	v_mov_b32_e32 v135, v132
	v_pk_add_f32 v[144:145], v[134:135], v[146:147] neg_lo:[0,1] neg_hi:[0,1]
	v_mov_b32_e32 v131, v136
	v_sub_f32_e32 v133, v134, v144
	v_pk_add_f32 v[130:131], v[130:131], v[144:145] neg_lo:[0,1] neg_hi:[0,1]
	v_sub_f32_e32 v133, v146, v133
	v_add_f32_e32 v130, v130, v133
	v_add_f32_e32 v130, v130, v131
	v_add_f32_e32 v130, v132, v130
	v_cndmask_b32_e32 v130, v159, v130, vcc
	v_cmp_ngt_f32_e32 vcc, -1.0, v139
	s_nop 1
	v_cndmask_b32_e32 v130, v160, v130, vcc
	v_cmp_neq_f32_e32 vcc, -1.0, v139
	s_nop 1
	v_cndmask_b32_e32 v130, v161, v130, vcc
	v_cmp_lt_f32_e64 vcc, |v139|, s12
	s_nop 1
	v_cndmask_b32_e32 v130, v130, v139, vcc

.LBB0_942:
	v_readlane_b32 s0, v255, 7
	s_cmp_eq_u32 s0, 0
	s_cbranch_scc1 .Lp3_done
	s_mov_b32 s0, 0
	s_mov_b32 s1, 1
	v_writelane_b32 v255, s0, 7
	v_writelane_b32 v255, s1, 1
	v_writelane_b32 v255, s0, 2
	v_readlane_b32 s91, v254, 46
	v_readlane_b32 s92, v254, 43
	v_readlane_b32 s93, v254, 44
	v_readlane_b32 s90, v254, 45
	v_readfirstlane_b32 s94, v0
	v_readlane_b32 s4, v254, 0
	v_readlane_b32 s5, v254, 1
	s_nop 3
	s_sub_u32 s4, s4, 0x118
	s_subb_u32 s5, s5, 0
	s_load_dwordx2 s[18:19], s[4:5], 0x88
	s_waitcnt lgkmcnt(0)
	s_branch .Lp3_again
